# rwkv mode-0 chunk scan rewritten: all token loads of a sub-block issued together and prefetched one sub-block ahead, 8-step sub-blocks
# speedup vs baseline: 1.0129x; 1.0129x over previous
; #define LAS __attribute__((address_space(3)))
; template <int MODE> __device__ __forceinline__ void rwkv_item(const Params& P, int e, int c, int h, LAS float* slab, int lane) {
;     ...
;     const float mu_r = P.in[I_AMU][(size_t)e * DINA + ch], mu_k = P.in[I_AMU][(size_t)e * DINA + 512 + ch];
;     const float kkw = P.in[I_AKK][e * 512 + ch], ka = P.in[I_AKA][e * 512 + ch], rk = P.in[I_ARK][e * 512 + ch];
;     const float lnw = P.in[I_ALNW][e * 512 + ch], lnb = P.in[I_ALNB][e * 512 + ch];
;     constexpr int SB = MODE == 0 ? 4 : 8;
;     f32x2 S2[32], C2[MODE == 0 ? 32 : 1];
;     const size_t rowoff = (((size_t)c * 8 + h) * 64 + lane) * 64;
;     if (MODE == 0) {
; #pragma unroll
;         for (int i = 0; i < 32; ++i) { S2[i] = (f32x2){(2 * i) == lane ? 1.f : 0.f, (2 * i + 1) == lane ? 1.f : 0.f}; C2[i] = (f32x2){0.f, 0.f}; }
;     } else {
; #pragma unroll
;         for (int q = 0; q < 16; ++q) { const f32x4 v = *(const f32x4*)(MCC + rowoff + 4 * q); S2[2 * q] = (f32x2){v.x, v.y}; S2[2 * q + 1] = (f32x2){v.z, v.w}; }
;     }
;     float r1[SB + 1], k1[SB + 1], vv[SB], dd[SB], aa[SB], gg[MODE == 1 ? SB : 1];
; template <int MODE> __device__ __forceinline__ void stage_rwkv_scan(const Params& P, int e, LAS unsigned char* lds) {
;     int tid = threadIdx.x; asm volatile("" : "+v"(tid)); const int lane = tid & 63, wave = __builtin_amdgcn_readfirstlane(tid >> 6);
;     LAS float* slab = (LAS float*)(lds + wave * 16384);
;     const int gw = blockIdx.x * NWAVES + wave, ngw = gridDim.x * NWAVES;
;     for (int it = gw; it < RNCH * 8; it += ngw) rwkv_item<MODE>(P, e, it >> 3, it & 7, slab, lane);
.LBB0_254:
	s_and_b64 vcc, exec, s[0:1]
	s_cbranch_vccz .LBB0_273
	s_cmp_gt_i32 s67, 3
	s_mov_b64 s[0:1], -1
	s_cbranch_scc0 .LBB0_772
	v_readlane_b32 s0, v255, 6
	v_readlane_b32 s1, v255, 7
	s_cmp_gt_i32 s0, 0
	s_cselect_b64 s[0:1], -1, 0
	v_writelane_b32 v255, s0, 17
	s_cmp_lt_i32 s67, 6
	s_nop 0
	v_writelane_b32 v255, s1, 18
	s_mov_b64 s[0:1], -1
	s_cbranch_scc1 .LBB0_574
	s_cmp_lt_i32 s67, 7
	s_cbranch_scc1 .LBB0_372
	s_cmp_gt_i32 s67, 7
	s_cbranch_scc0 .LBB0_269
	v_readlane_b32 s0, v254, 63
	v_readlane_b32 s1, v255, 0
	s_andn2_b64 vcc, exec, s[0:1]
	s_cbranch_vccnz .LBB0_268
	v_mov_b32_e32 v0, v211
	s_nop 0
	v_readfirstlane_b32 s0, v0
	s_ashr_i32 s0, s0, 6
	s_add_i32 s20, s0, s55
	s_cmpk_gt_i32 s20, 0x7ff
	s_cbranch_scc1 .LBB0_268
	v_and_b32_e32 v128, 63, v0
	s_lshl_b32 s0, s0, 14
	s_add_i32 s21, s0, 0
	s_load_dwordx2 s[0:1], s[30:31], 0x38
	s_load_dwordx4 s[4:7], s[30:31], 0x68
	s_waitcnt lgkmcnt(0)
	s_add_u32 s8, s72, 0x12880000
	s_addc_u32 s9, s73, 0
	s_add_u32 s10, s72, 0xb880000
	s_addc_u32 s11, s73, 0
	v_readlane_b32 s2, v255, 5
	s_add_u32 s12, s0, s2
	v_readlane_b32 s0, v255, 4
	s_addc_u32 s13, s1, s0
	s_add_u32 s14, s72, 0xd880000
	s_addc_u32 s15, s73, 0
	v_readlane_b32 s0, v255, 3
	s_add_u32 s16, s72, s0
	s_addc_u32 s17, s73, 0
	s_add_u32 s18, s72, 0x10880000
	s_addc_u32 s19, s73, 0
	v_readlane_b32 s26, v254, 55
	v_readlane_b32 s27, v254, 56
	s_waitcnt vmcnt(0)
	v_lshl_add_u32 v129, v128, 2, s21
.LBB0_262:
	s_and_b32 s22, s20, 7
	s_lshl_b32 s22, s22, 6
	s_ashr_i32 s0, s20, 3
	s_lshl_b32 s1, s0, 6
	v_readlane_b32 s2, v255, 8
	v_or_b32_e32 v210, s22, v128
	v_lshlrev_b32_e32 v207, 2, v210
	global_load_dword v230, v207, s[12:13] offset:2048
	v_or_b32_e32 v204, s2, v210
	v_lshlrev_b32_e32 v204, 2, v204
	global_load_dword v231, v204, s[4:5]
	global_load_dword v232, v204, s[6:7]
	s_mul_i32 s2, s1, 0xe00
	s_add_i32 s2, s2, 0x400
	v_lshl_add_u32 v201, v210, 1, s2
	s_lshl_b32 s2, s1, 10
	v_lshl_add_u32 v202, v210, 1, s2
	s_lshl_b32 s2, s1, 11
	v_lshl_add_u32 v203, v210, 2, s2
	s_cmp_eq_u32 s0, 0
	s_cselect_b32 s2, 0, 0xe00
	v_subrev_u32_e32 v204, s2, v201
	global_load_ushort v200, v204, s[26:27]
	global_load_ushort v168, v201, s[26:27]
	global_load_ushort v169, v201, s[26:27] offset:3584
	v_add_u32_e32 v204, 0x1c00, v201
	v_add_u32_e32 v205, 0x3800, v201
	v_add_u32_e32 v206, 0x5400, v201
	global_load_ushort v170, v204, s[26:27]
	global_load_ushort v171, v204, s[26:27] offset:3584
	global_load_ushort v172, v205, s[26:27]
	global_load_ushort v173, v205, s[26:27] offset:3584
	global_load_ushort v174, v206, s[26:27]
	global_load_ushort v175, v206, s[26:27] offset:3584
	v_add_u32_e32 v204, 0x1000, v202
	global_load_ushort v176, v202, s[14:15]
	global_load_ushort v177, v202, s[14:15] offset:1024
	global_load_ushort v178, v202, s[14:15] offset:2048
	global_load_ushort v179, v202, s[14:15] offset:3072
	global_load_ushort v180, v204, s[14:15]
	global_load_ushort v181, v204, s[14:15] offset:1024
	global_load_ushort v182, v204, s[14:15] offset:2048
	global_load_ushort v183, v204, s[14:15] offset:3072
	global_load_ushort v192, v202, s[16:17]
	global_load_ushort v193, v202, s[16:17] offset:1024
	global_load_ushort v194, v202, s[16:17] offset:2048
	global_load_ushort v195, v202, s[16:17] offset:3072
	global_load_ushort v196, v204, s[16:17]
	global_load_ushort v197, v204, s[16:17] offset:1024
	global_load_ushort v198, v204, s[16:17] offset:2048
	global_load_ushort v199, v204, s[16:17] offset:3072
	v_add_u32_e32 v205, 0x1000, v203
	v_add_u32_e32 v206, 0x2000, v203
	v_add_u32_e32 v207, 0x3000, v203
	global_load_dword v184, v203, s[10:11]
	global_load_dword v185, v203, s[10:11] offset:2048
	global_load_dword v186, v205, s[10:11]
	global_load_dword v187, v205, s[10:11] offset:2048
	global_load_dword v188, v206, s[10:11]
	global_load_dword v189, v206, s[10:11] offset:2048
	global_load_dword v190, v207, s[10:11]
	global_load_dword v191, v207, s[10:11] offset:2048
	v_add_u32_e32 v201, 0x7000, v201
	v_add_u32_e32 v202, 0x2000, v202
	v_add_u32_e32 v203, 0x4000, v203
	v_cmp_eq_u32_e32 vcc, 0, v128
	v_mov_b32_e32 v124, 0
	s_nop 0
	v_cndmask_b32_e64 v112, 0, 1.0, vcc
	v_cmp_eq_u32_e32 vcc, 1, v128
	v_mov_b32_e32 v125, 0
	s_nop 0
	v_cndmask_b32_e64 v113, 0, 1.0, vcc
	v_cmp_eq_u32_e32 vcc, 2, v128
	v_mov_b32_e32 v126, 0
	s_nop 0
	v_cndmask_b32_e64 v114, 0, 1.0, vcc
	v_cmp_eq_u32_e32 vcc, 3, v128
	v_mov_b32_e32 v127, 0
	s_nop 0
	v_cndmask_b32_e64 v115, 0, 1.0, vcc
	v_cmp_eq_u32_e32 vcc, 4, v128
	v_mov_b32_e32 v120, 0
	s_nop 0
	v_cndmask_b32_e64 v104, 0, 1.0, vcc
	v_cmp_eq_u32_e32 vcc, 5, v128
	v_mov_b32_e32 v121, 0
	s_nop 0
	v_cndmask_b32_e64 v105, 0, 1.0, vcc
	v_cmp_eq_u32_e32 vcc, 6, v128
	v_mov_b32_e32 v122, 0
	s_nop 0
	v_cndmask_b32_e64 v106, 0, 1.0, vcc
	v_cmp_eq_u32_e32 vcc, 7, v128
	v_mov_b32_e32 v123, 0
	s_nop 0
	v_cndmask_b32_e64 v107, 0, 1.0, vcc
	v_cmp_eq_u32_e32 vcc, 8, v128
	v_mov_b32_e32 v116, 0
	s_nop 0
	v_cndmask_b32_e64 v92, 0, 1.0, vcc
	v_cmp_eq_u32_e32 vcc, 9, v128
	v_mov_b32_e32 v117, 0
	s_nop 0
	v_cndmask_b32_e64 v93, 0, 1.0, vcc
	v_cmp_eq_u32_e32 vcc, 10, v128
	v_mov_b32_e32 v118, 0
	s_nop 0
	v_cndmask_b32_e64 v94, 0, 1.0, vcc
	v_cmp_eq_u32_e32 vcc, 11, v128
	v_mov_b32_e32 v119, 0
	s_nop 0
	v_cndmask_b32_e64 v95, 0, 1.0, vcc
	v_cmp_eq_u32_e32 vcc, 12, v128
	v_mov_b32_e32 v108, 0
	s_nop 0
	v_cndmask_b32_e64 v76, 0, 1.0, vcc
	v_cmp_eq_u32_e32 vcc, 13, v128
	v_mov_b32_e32 v109, 0
	s_nop 0
	v_cndmask_b32_e64 v77, 0, 1.0, vcc
	v_cmp_eq_u32_e32 vcc, 14, v128
	v_mov_b32_e32 v110, 0
	s_nop 0
	v_cndmask_b32_e64 v78, 0, 1.0, vcc
	v_cmp_eq_u32_e32 vcc, 15, v128
	v_mov_b32_e32 v111, 0
	s_nop 0
	v_cndmask_b32_e64 v79, 0, 1.0, vcc
	v_cmp_eq_u32_e32 vcc, 16, v128
; template <int MODE> __device__ __forceinline__ void rwkv_item(const Params& P, int e, int c, int h, LAS float* slab, int lane) {
;     ...
;     if (MODE == 0) {
; #pragma unroll
;         for (int i = 0; i < 32; ++i) { S2[i] = (f32x2){(2 * i) == lane ? 1.f : 0.f, (2 * i + 1) == lane ? 1.f : 0.f}; C2[i] = (f32x2){0.f, 0.f}; }
;     } else {
; #pragma unroll
;         for (int q = 0; q < 16; ++q) { const f32x4 v = *(const f32x4*)(MCC + rowoff + 4 * q); S2[2 * q] = (f32x2){v.x, v.y}; S2[2 * q + 1] = (f32x2){v.z, v.w}; }
;     }
;     float r1[SB + 1], k1[SB + 1], vv[SB], dd[SB], aa[SB], gg[MODE == 1 ? SB : 1];
	v_mov_b32_e32 v96, 0
	s_nop 0
	v_cndmask_b32_e64 v64, 0, 1.0, vcc
	v_cmp_eq_u32_e32 vcc, 17, v128
	v_mov_b32_e32 v97, 0
	s_nop 0
	v_cndmask_b32_e64 v65, 0, 1.0, vcc
	v_cmp_eq_u32_e32 vcc, 18, v128
	v_mov_b32_e32 v98, 0
	s_nop 0
	v_cndmask_b32_e64 v66, 0, 1.0, vcc
	v_cmp_eq_u32_e32 vcc, 19, v128
	v_mov_b32_e32 v99, 0
	s_nop 0
	v_cndmask_b32_e64 v67, 0, 1.0, vcc
	v_cmp_eq_u32_e32 vcc, 20, v128
	v_mov_b32_e32 v80, 0
	s_nop 0
	v_cndmask_b32_e64 v100, 0, 1.0, vcc
	v_cmp_eq_u32_e32 vcc, 21, v128
	v_mov_b32_e32 v81, 0
	s_nop 0
	v_cndmask_b32_e64 v101, 0, 1.0, vcc
	v_cmp_eq_u32_e32 vcc, 22, v128
	v_mov_b32_e32 v82, 0
	s_nop 0
	v_cndmask_b32_e64 v102, 0, 1.0, vcc
	v_cmp_eq_u32_e32 vcc, 23, v128
	v_mov_b32_e32 v83, 0
	s_nop 0
	v_cndmask_b32_e64 v103, 0, 1.0, vcc
	v_cmp_eq_u32_e32 vcc, 24, v128
	v_mov_b32_e32 v68, 0
	s_nop 0
	v_cndmask_b32_e64 v88, 0, 1.0, vcc
	v_cmp_eq_u32_e32 vcc, 25, v128
	v_mov_b32_e32 v69, 0
	s_nop 0
	v_cndmask_b32_e64 v89, 0, 1.0, vcc
	v_cmp_eq_u32_e32 vcc, 26, v128
	v_mov_b32_e32 v70, 0
	s_nop 0
	v_cndmask_b32_e64 v90, 0, 1.0, vcc
	v_cmp_eq_u32_e32 vcc, 27, v128
	v_mov_b32_e32 v71, 0
	s_nop 0
	v_cndmask_b32_e64 v91, 0, 1.0, vcc
	v_cmp_eq_u32_e32 vcc, 28, v128
	v_mov_b32_e32 v52, 0
	s_nop 0
	v_cndmask_b32_e64 v84, 0, 1.0, vcc
	v_cmp_eq_u32_e32 vcc, 29, v128
	v_mov_b32_e32 v53, 0
	s_nop 0
	v_cndmask_b32_e64 v85, 0, 1.0, vcc
	v_cmp_eq_u32_e32 vcc, 30, v128
	v_mov_b32_e32 v54, 0
	s_nop 0
	v_cndmask_b32_e64 v86, 0, 1.0, vcc
	v_cmp_eq_u32_e32 vcc, 31, v128
	v_mov_b32_e32 v55, 0
	s_nop 0
	v_cndmask_b32_e64 v87, 0, 1.0, vcc
	v_cmp_eq_u32_e32 vcc, 32, v128
	v_mov_b32_e32 v44, 0
	s_nop 0
	v_cndmask_b32_e64 v72, 0, 1.0, vcc
	v_cmp_eq_u32_e32 vcc, 33, v128
	v_mov_b32_e32 v45, 0
	s_nop 0
	v_cndmask_b32_e64 v73, 0, 1.0, vcc
	v_cmp_eq_u32_e32 vcc, 34, v128
	v_mov_b32_e32 v46, 0
	s_nop 0
	v_cndmask_b32_e64 v74, 0, 1.0, vcc
	v_cmp_eq_u32_e32 vcc, 35, v128
	v_mov_b32_e32 v47, 0
	s_nop 0
	v_cndmask_b32_e64 v75, 0, 1.0, vcc
	v_cmp_eq_u32_e32 vcc, 36, v128
	v_mov_b32_e32 v32, 0
	s_nop 0
	v_cndmask_b32_e64 v60, 0, 1.0, vcc
	v_cmp_eq_u32_e32 vcc, 37, v128
	v_mov_b32_e32 v33, 0
	s_nop 0
	v_cndmask_b32_e64 v61, 0, 1.0, vcc
	v_cmp_eq_u32_e32 vcc, 38, v128
	v_mov_b32_e32 v34, 0
	s_nop 0
	v_cndmask_b32_e64 v62, 0, 1.0, vcc
	v_cmp_eq_u32_e32 vcc, 39, v128
	v_mov_b32_e32 v35, 0
	s_nop 0
	v_cndmask_b32_e64 v63, 0, 1.0, vcc
	v_cmp_eq_u32_e32 vcc, 40, v128
	v_mov_b32_e32 v24, 0
	s_nop 0
	v_cndmask_b32_e64 v56, 0, 1.0, vcc
	v_cmp_eq_u32_e32 vcc, 41, v128
	v_mov_b32_e32 v25, 0
	s_nop 0
	v_cndmask_b32_e64 v57, 0, 1.0, vcc
	v_cmp_eq_u32_e32 vcc, 42, v128
	v_mov_b32_e32 v26, 0
	s_nop 0
	v_cndmask_b32_e64 v58, 0, 1.0, vcc
	v_cmp_eq_u32_e32 vcc, 43, v128
	v_mov_b32_e32 v27, 0
	s_nop 0
	v_cndmask_b32_e64 v59, 0, 1.0, vcc
	v_cmp_eq_u32_e32 vcc, 44, v128
	v_mov_b32_e32 v16, 0
	s_nop 0
	v_cndmask_b32_e64 v48, 0, 1.0, vcc
	v_cmp_eq_u32_e32 vcc, 45, v128
	v_mov_b32_e32 v17, 0
	s_nop 0
	v_cndmask_b32_e64 v49, 0, 1.0, vcc
	v_cmp_eq_u32_e32 vcc, 46, v128
	v_mov_b32_e32 v18, 0
	s_nop 0
	v_cndmask_b32_e64 v50, 0, 1.0, vcc
	v_cmp_eq_u32_e32 vcc, 47, v128
	v_mov_b32_e32 v19, 0
	s_nop 0
	v_cndmask_b32_e64 v51, 0, 1.0, vcc
	v_cmp_eq_u32_e32 vcc, 48, v128
	v_mov_b32_e32 v12, 0
	s_nop 0
	v_cndmask_b32_e64 v40, 0, 1.0, vcc
	v_cmp_eq_u32_e32 vcc, 49, v128
	v_mov_b32_e32 v13, 0
	s_nop 0
	v_cndmask_b32_e64 v41, 0, 1.0, vcc
	v_cmp_eq_u32_e32 vcc, 50, v128
	v_mov_b32_e32 v14, 0
	s_nop 0
	v_cndmask_b32_e64 v42, 0, 1.0, vcc
	v_cmp_eq_u32_e32 vcc, 51, v128
	v_mov_b32_e32 v15, 0
	s_nop 0
	v_cndmask_b32_e64 v43, 0, 1.0, vcc
	v_cmp_eq_u32_e32 vcc, 52, v128
	v_mov_b32_e32 v8, 0
	s_nop 0
	v_cndmask_b32_e64 v36, 0, 1.0, vcc
	v_cmp_eq_u32_e32 vcc, 53, v128
	v_mov_b32_e32 v9, 0
	s_nop 0
	v_cndmask_b32_e64 v37, 0, 1.0, vcc
	v_cmp_eq_u32_e32 vcc, 54, v128
	v_mov_b32_e32 v10, 0
	s_nop 0
	v_cndmask_b32_e64 v38, 0, 1.0, vcc
	v_cmp_eq_u32_e32 vcc, 55, v128
	v_mov_b32_e32 v11, 0
	s_nop 0
	v_cndmask_b32_e64 v39, 0, 1.0, vcc
	v_cmp_eq_u32_e32 vcc, 56, v128
	v_mov_b32_e32 v4, 0
	s_nop 0
	v_cndmask_b32_e64 v28, 0, 1.0, vcc
	v_cmp_eq_u32_e32 vcc, 57, v128
	v_mov_b32_e32 v5, 0
	s_nop 0
	v_cndmask_b32_e64 v29, 0, 1.0, vcc
	v_cmp_eq_u32_e32 vcc, 58, v128
	v_mov_b32_e32 v6, 0
	s_nop 0
	v_cndmask_b32_e64 v30, 0, 1.0, vcc
	v_cmp_eq_u32_e32 vcc, 59, v128
	v_mov_b32_e32 v7, 0
	s_nop 0
	v_cndmask_b32_e64 v31, 0, 1.0, vcc
	v_cmp_eq_u32_e32 vcc, 60, v128
	v_mov_b32_e32 v0, 0
	s_nop 0
	v_cndmask_b32_e64 v20, 0, 1.0, vcc
	v_cmp_eq_u32_e32 vcc, 61, v128
	v_mov_b32_e32 v1, 0
	s_nop 0
	v_cndmask_b32_e64 v21, 0, 1.0, vcc
	v_cmp_eq_u32_e32 vcc, 62, v128
	v_mov_b32_e32 v2, 0
	s_nop 0
	v_cndmask_b32_e64 v22, 0, 1.0, vcc
	v_cmp_eq_u32_e32 vcc, 63, v128
	v_mov_b32_e32 v3, 0
	s_nop 0
	v_cndmask_b32_e64 v23, 0, 1.0, vcc
	s_mov_b32 s23, 0
	s_cmp_gt_i32 s0, 0
	s_cselect_b64 vcc, -1, 0
	s_waitcnt vmcnt(32)
	v_lshlrev_b32_e32 v200, 16, v200
	v_cndmask_b32_e32 v200, 0, v200, vcc
; #define LAS __attribute__((address_space(3)))
; __device__ __forceinline__ float frsq(float x) { return __builtin_amdgcn_rsqf(x); }
; template <int MODE> __device__ __forceinline__ void rwkv_item(const Params& P, int e, int c, int h, LAS float* slab, int lane) {
;     ...
; #pragma unroll
;         for (int s = 0; s < SB; ++s) {
;             const float r = r1[s + 1] + (r1[s] - r1[s + 1]) * mu_r, k = k1[s + 1] + (k1[s] - k1[s + 1]) * mu_k, a = aa[s];
;             float kk = k * kkw;
;             const float ss = wave_sum(kk * kk);
;             kk *= frsq(fmaxf(ss, 1e-24f));
;             const float b = kk * a, kp = k * (1.f + (a - 1.f) * ka);
;             LAS float* st = slab + s * 512;
;             st[lane] = dd[s]; st[64 + lane] = kk; st[128 + lane] = b; st[192 + lane] = kp; st[256 + lane] = r; st[320 + lane] = vv[s];
;             if (MODE == 1) { st[384 + lane] = wave_sum(r * kp * rk); st[448 + lane] = gg[s]; }
;         }
.Lm0_sub:
	s_waitcnt vmcnt(0)
	v_lshlrev_b32_e32 v136, 16, v168
	v_sub_f32_e32 v130, v200, v136
	v_fma_f32 v130, v230, v130, v136
	v_mul_f32_e32 v131, v231, v130
	v_mul_f32_e32 v132, v131, v131
	v_lshlrev_b32_e32 v134, 16, v176
	v_lshlrev_b32_e32 v135, 16, v192
	v_mov_b32_dpp v132, v132 quad_perm:[1,0,3,2] row_mask:0xf bank_mask:0xf bound_ctrl:1
	v_fmac_f32_e32 v132, v131, v131
	v_mov_b32_e32 v200, v136
	s_nop 0
	v_add_f32_dpp v132, v132, v132 quad_perm:[2,3,0,1] row_mask:0xf bank_mask:0xf bound_ctrl:1
	s_nop 1
	v_add_f32_dpp v132, v132, v132 row_half_mirror row_mask:0xf bank_mask:0xf bound_ctrl:1
	s_nop 1
	v_add_f32_dpp v132, v132, v132 row_mirror row_mask:0xf bank_mask:0xf bound_ctrl:1
	s_nop 0
	v_readlane_b32 s3, v132, 16
	v_readlane_b32 s25, v132, 48
	v_readlane_b32 s2, v132, 0
	v_readlane_b32 s24, v132, 32
	v_mov_b32_e32 v132, s3
	v_mov_b32_e32 v133, s25
	v_add_f32_e32 v132, s2, v132
	v_add_f32_e32 v133, s24, v133
	v_add_f32_e32 v132, v132, v133
	v_max_f32_e32 v132, 0x179abe15, v132
	v_rsq_f32_e32 v132, v132
	v_add_f32_e32 v133, -1.0, v134
	v_fma_f32 v133, v232, v133, 1.0
	v_mul_f32_e32 v130, v130, v133
	v_mul_f32_e32 v131, v131, v132
	v_mul_f32_e32 v132, v131, v134
	ds_write2st64_b32 v129, v184, v131 offset0:0 offset1:1
	ds_write2st64_b32 v129, v132, v130 offset0:2 offset1:3
	ds_write_b32 v129, v135 offset:1280
	v_lshlrev_b32_e32 v136, 16, v169
	v_sub_f32_e32 v130, v200, v136
	v_fma_f32 v130, v230, v130, v136
	v_mul_f32_e32 v131, v231, v130
	v_mul_f32_e32 v132, v131, v131
	v_lshlrev_b32_e32 v134, 16, v177
	v_lshlrev_b32_e32 v135, 16, v193
	v_mov_b32_dpp v132, v132 quad_perm:[1,0,3,2] row_mask:0xf bank_mask:0xf bound_ctrl:1
	v_fmac_f32_e32 v132, v131, v131
	v_mov_b32_e32 v200, v136
	s_nop 0
	v_add_f32_dpp v132, v132, v132 quad_perm:[2,3,0,1] row_mask:0xf bank_mask:0xf bound_ctrl:1
	s_nop 1
	v_add_f32_dpp v132, v132, v132 row_half_mirror row_mask:0xf bank_mask:0xf bound_ctrl:1
	s_nop 1
	v_add_f32_dpp v132, v132, v132 row_mirror row_mask:0xf bank_mask:0xf bound_ctrl:1
	s_nop 0
	v_readlane_b32 s3, v132, 16
	v_readlane_b32 s25, v132, 48
	v_readlane_b32 s2, v132, 0
	v_readlane_b32 s24, v132, 32
	v_mov_b32_e32 v132, s3
	v_mov_b32_e32 v133, s25
	v_add_f32_e32 v132, s2, v132
	v_add_f32_e32 v133, s24, v133
	v_add_f32_e32 v132, v132, v133
	v_max_f32_e32 v132, 0x179abe15, v132
	v_rsq_f32_e32 v132, v132
	v_add_f32_e32 v133, -1.0, v134
	v_fma_f32 v133, v232, v133, 1.0
	v_mul_f32_e32 v130, v130, v133
	v_mul_f32_e32 v131, v131, v132
	v_mul_f32_e32 v132, v131, v134
	ds_write2st64_b32 v129, v185, v131 offset0:8 offset1:9
	ds_write2st64_b32 v129, v132, v130 offset0:10 offset1:11
	ds_write_b32 v129, v135 offset:3328
	v_lshlrev_b32_e32 v136, 16, v170
	v_sub_f32_e32 v130, v200, v136
	v_fma_f32 v130, v230, v130, v136
	v_mul_f32_e32 v131, v231, v130
	v_mul_f32_e32 v132, v131, v131
	v_lshlrev_b32_e32 v134, 16, v178
	v_lshlrev_b32_e32 v135, 16, v194
	v_mov_b32_dpp v132, v132 quad_perm:[1,0,3,2] row_mask:0xf bank_mask:0xf bound_ctrl:1
	v_fmac_f32_e32 v132, v131, v131
	v_mov_b32_e32 v200, v136
	s_nop 0
	v_add_f32_dpp v132, v132, v132 quad_perm:[2,3,0,1] row_mask:0xf bank_mask:0xf bound_ctrl:1
	s_nop 1
	v_add_f32_dpp v132, v132, v132 row_half_mirror row_mask:0xf bank_mask:0xf bound_ctrl:1
	s_nop 1
	v_add_f32_dpp v132, v132, v132 row_mirror row_mask:0xf bank_mask:0xf bound_ctrl:1
	s_nop 0
	v_readlane_b32 s3, v132, 16
	v_readlane_b32 s25, v132, 48
	v_readlane_b32 s2, v132, 0
	v_readlane_b32 s24, v132, 32
	v_mov_b32_e32 v132, s3
	v_mov_b32_e32 v133, s25
	v_add_f32_e32 v132, s2, v132
	v_add_f32_e32 v133, s24, v133
	v_add_f32_e32 v132, v132, v133
	v_max_f32_e32 v132, 0x179abe15, v132
	v_rsq_f32_e32 v132, v132
	v_add_f32_e32 v133, -1.0, v134
	v_fma_f32 v133, v232, v133, 1.0
	v_mul_f32_e32 v130, v130, v133
	v_mul_f32_e32 v131, v131, v132
	v_mul_f32_e32 v132, v131, v134
	ds_write2st64_b32 v129, v186, v131 offset0:16 offset1:17
	ds_write2st64_b32 v129, v132, v130 offset0:18 offset1:19
	ds_write_b32 v129, v135 offset:5376
	v_lshlrev_b32_e32 v136, 16, v171
	v_sub_f32_e32 v130, v200, v136
	v_fma_f32 v130, v230, v130, v136
	v_mul_f32_e32 v131, v231, v130
	v_mul_f32_e32 v132, v131, v131
	v_lshlrev_b32_e32 v134, 16, v179
	v_lshlrev_b32_e32 v135, 16, v195
	v_mov_b32_dpp v132, v132 quad_perm:[1,0,3,2] row_mask:0xf bank_mask:0xf bound_ctrl:1
	v_fmac_f32_e32 v132, v131, v131
	v_mov_b32_e32 v200, v136
	s_nop 0
	v_add_f32_dpp v132, v132, v132 quad_perm:[2,3,0,1] row_mask:0xf bank_mask:0xf bound_ctrl:1
	s_nop 1
	v_add_f32_dpp v132, v132, v132 row_half_mirror row_mask:0xf bank_mask:0xf bound_ctrl:1
	s_nop 1
	v_add_f32_dpp v132, v132, v132 row_mirror row_mask:0xf bank_mask:0xf bound_ctrl:1
	s_nop 0
	v_readlane_b32 s3, v132, 16
	v_readlane_b32 s25, v132, 48
	v_readlane_b32 s2, v132, 0
	v_readlane_b32 s24, v132, 32
	v_mov_b32_e32 v132, s3
	v_mov_b32_e32 v133, s25
	v_add_f32_e32 v132, s2, v132
	v_add_f32_e32 v133, s24, v133
	v_add_f32_e32 v132, v132, v133
	v_max_f32_e32 v132, 0x179abe15, v132
	v_rsq_f32_e32 v132, v132
	v_add_f32_e32 v133, -1.0, v134
	v_fma_f32 v133, v232, v133, 1.0
	v_mul_f32_e32 v130, v130, v133
	v_mul_f32_e32 v131, v131, v132
	v_mul_f32_e32 v132, v131, v134
	ds_write2st64_b32 v129, v187, v131 offset0:24 offset1:25
	ds_write2st64_b32 v129, v132, v130 offset0:26 offset1:27
	ds_write_b32 v129, v135 offset:7424
	v_lshlrev_b32_e32 v136, 16, v172
	v_sub_f32_e32 v130, v200, v136
	v_fma_f32 v130, v230, v130, v136
	v_mul_f32_e32 v131, v231, v130
	v_mul_f32_e32 v132, v131, v131
	v_lshlrev_b32_e32 v134, 16, v180
	v_lshlrev_b32_e32 v135, 16, v196
	v_mov_b32_dpp v132, v132 quad_perm:[1,0,3,2] row_mask:0xf bank_mask:0xf bound_ctrl:1
	v_fmac_f32_e32 v132, v131, v131
; #define LAS __attribute__((address_space(3)))
; __device__ __forceinline__ float frsq(float x) { return __builtin_amdgcn_rsqf(x); }
; #define LDS_WAIT() asm volatile("s_waitcnt lgkmcnt(0)" ::: "memory")
; template <int MODE> __device__ __forceinline__ void rwkv_item(const Params& P, int e, int c, int h, LAS float* slab, int lane) {
;     ...
; #pragma unroll
;         for (int s = 0; s < SB; ++s) {
;             const float r = r1[s + 1] + (r1[s] - r1[s + 1]) * mu_r, k = k1[s + 1] + (k1[s] - k1[s + 1]) * mu_k, a = aa[s];
;             float kk = k * kkw;
;             const float ss = wave_sum(kk * kk);
;             kk *= frsq(fmaxf(ss, 1e-24f));
;             const float b = kk * a, kp = k * (1.f + (a - 1.f) * ka);
;             LAS float* st = slab + s * 512;
;             st[lane] = dd[s]; st[64 + lane] = kk; st[128 + lane] = b; st[192 + lane] = kp; st[256 + lane] = r; st[320 + lane] = vv[s];
;             if (MODE == 1) { st[384 + lane] = wave_sum(r * kp * rk); st[448 + lane] = gg[s]; }
;         }
;         LDS_WAIT();
;         if (MODE == 1 && sb + 1 < RLCH / SB) RW_LOAD(tb + SB);
	v_mov_b32_e32 v200, v136
	s_nop 0
	v_add_f32_dpp v132, v132, v132 quad_perm:[2,3,0,1] row_mask:0xf bank_mask:0xf bound_ctrl:1
	s_nop 1
	v_add_f32_dpp v132, v132, v132 row_half_mirror row_mask:0xf bank_mask:0xf bound_ctrl:1
	s_nop 1
	v_add_f32_dpp v132, v132, v132 row_mirror row_mask:0xf bank_mask:0xf bound_ctrl:1
	s_nop 0
	v_readlane_b32 s3, v132, 16
	v_readlane_b32 s25, v132, 48
	v_readlane_b32 s2, v132, 0
	v_readlane_b32 s24, v132, 32
	v_mov_b32_e32 v132, s3
	v_mov_b32_e32 v133, s25
	v_add_f32_e32 v132, s2, v132
	v_add_f32_e32 v133, s24, v133
	v_add_f32_e32 v132, v132, v133
	v_max_f32_e32 v132, 0x179abe15, v132
	v_rsq_f32_e32 v132, v132
	v_add_f32_e32 v133, -1.0, v134
	v_fma_f32 v133, v232, v133, 1.0
	v_mul_f32_e32 v130, v130, v133
	v_mul_f32_e32 v131, v131, v132
	v_mul_f32_e32 v132, v131, v134
	ds_write2st64_b32 v129, v188, v131 offset0:32 offset1:33
	ds_write2st64_b32 v129, v132, v130 offset0:34 offset1:35
	ds_write_b32 v129, v135 offset:9472
	v_lshlrev_b32_e32 v136, 16, v173
	v_sub_f32_e32 v130, v200, v136
	v_fma_f32 v130, v230, v130, v136
	v_mul_f32_e32 v131, v231, v130
	v_mul_f32_e32 v132, v131, v131
	v_lshlrev_b32_e32 v134, 16, v181
	v_lshlrev_b32_e32 v135, 16, v197
	v_mov_b32_dpp v132, v132 quad_perm:[1,0,3,2] row_mask:0xf bank_mask:0xf bound_ctrl:1
	v_fmac_f32_e32 v132, v131, v131
	v_mov_b32_e32 v200, v136
	s_nop 0
	v_add_f32_dpp v132, v132, v132 quad_perm:[2,3,0,1] row_mask:0xf bank_mask:0xf bound_ctrl:1
	s_nop 1
	v_add_f32_dpp v132, v132, v132 row_half_mirror row_mask:0xf bank_mask:0xf bound_ctrl:1
	s_nop 1
	v_add_f32_dpp v132, v132, v132 row_mirror row_mask:0xf bank_mask:0xf bound_ctrl:1
	s_nop 0
	v_readlane_b32 s3, v132, 16
	v_readlane_b32 s25, v132, 48
	v_readlane_b32 s2, v132, 0
	v_readlane_b32 s24, v132, 32
	v_mov_b32_e32 v132, s3
	v_mov_b32_e32 v133, s25
	v_add_f32_e32 v132, s2, v132
	v_add_f32_e32 v133, s24, v133
	v_add_f32_e32 v132, v132, v133
	v_max_f32_e32 v132, 0x179abe15, v132
	v_rsq_f32_e32 v132, v132
	v_add_f32_e32 v133, -1.0, v134
	v_fma_f32 v133, v232, v133, 1.0
	v_mul_f32_e32 v130, v130, v133
	v_mul_f32_e32 v131, v131, v132
	v_mul_f32_e32 v132, v131, v134
	ds_write2st64_b32 v129, v189, v131 offset0:40 offset1:41
	ds_write2st64_b32 v129, v132, v130 offset0:42 offset1:43
	ds_write_b32 v129, v135 offset:11520
	v_lshlrev_b32_e32 v136, 16, v174
	v_sub_f32_e32 v130, v200, v136
	v_fma_f32 v130, v230, v130, v136
	v_mul_f32_e32 v131, v231, v130
	v_mul_f32_e32 v132, v131, v131
	v_lshlrev_b32_e32 v134, 16, v182
	v_lshlrev_b32_e32 v135, 16, v198
	v_mov_b32_dpp v132, v132 quad_perm:[1,0,3,2] row_mask:0xf bank_mask:0xf bound_ctrl:1
	v_fmac_f32_e32 v132, v131, v131
	v_mov_b32_e32 v200, v136
	s_nop 0
	v_add_f32_dpp v132, v132, v132 quad_perm:[2,3,0,1] row_mask:0xf bank_mask:0xf bound_ctrl:1
	s_nop 1
	v_add_f32_dpp v132, v132, v132 row_half_mirror row_mask:0xf bank_mask:0xf bound_ctrl:1
	s_nop 1
	v_add_f32_dpp v132, v132, v132 row_mirror row_mask:0xf bank_mask:0xf bound_ctrl:1
	s_nop 0
	v_readlane_b32 s3, v132, 16
	v_readlane_b32 s25, v132, 48
	v_readlane_b32 s2, v132, 0
	v_readlane_b32 s24, v132, 32
	v_mov_b32_e32 v132, s3
	v_mov_b32_e32 v133, s25
	v_add_f32_e32 v132, s2, v132
	v_add_f32_e32 v133, s24, v133
	v_add_f32_e32 v132, v132, v133
	v_max_f32_e32 v132, 0x179abe15, v132
	v_rsq_f32_e32 v132, v132
	v_add_f32_e32 v133, -1.0, v134
	v_fma_f32 v133, v232, v133, 1.0
	v_mul_f32_e32 v130, v130, v133
	v_mul_f32_e32 v131, v131, v132
	v_mul_f32_e32 v132, v131, v134
	ds_write2st64_b32 v129, v190, v131 offset0:48 offset1:49
	ds_write2st64_b32 v129, v132, v130 offset0:50 offset1:51
	ds_write_b32 v129, v135 offset:13568
	v_lshlrev_b32_e32 v136, 16, v175
	v_sub_f32_e32 v130, v200, v136
	v_fma_f32 v130, v230, v130, v136
	v_mul_f32_e32 v131, v231, v130
	v_mul_f32_e32 v132, v131, v131
	v_lshlrev_b32_e32 v134, 16, v183
	v_lshlrev_b32_e32 v135, 16, v199
	v_mov_b32_dpp v132, v132 quad_perm:[1,0,3,2] row_mask:0xf bank_mask:0xf bound_ctrl:1
	v_fmac_f32_e32 v132, v131, v131
	v_mov_b32_e32 v200, v136
	s_nop 0
	v_add_f32_dpp v132, v132, v132 quad_perm:[2,3,0,1] row_mask:0xf bank_mask:0xf bound_ctrl:1
	s_nop 1
	v_add_f32_dpp v132, v132, v132 row_half_mirror row_mask:0xf bank_mask:0xf bound_ctrl:1
	s_nop 1
	v_add_f32_dpp v132, v132, v132 row_mirror row_mask:0xf bank_mask:0xf bound_ctrl:1
	s_nop 0
	v_readlane_b32 s3, v132, 16
	v_readlane_b32 s25, v132, 48
	v_readlane_b32 s2, v132, 0
	v_readlane_b32 s24, v132, 32
	v_mov_b32_e32 v132, s3
	v_mov_b32_e32 v133, s25
	v_add_f32_e32 v132, s2, v132
	v_add_f32_e32 v133, s24, v133
	v_add_f32_e32 v132, v132, v133
	v_max_f32_e32 v132, 0x179abe15, v132
	v_rsq_f32_e32 v132, v132
	v_add_f32_e32 v133, -1.0, v134
	v_fma_f32 v133, v232, v133, 1.0
	v_mul_f32_e32 v130, v130, v133
	v_mul_f32_e32 v131, v131, v132
	v_mul_f32_e32 v132, v131, v134
	ds_write2st64_b32 v129, v191, v131 offset0:56 offset1:57
	ds_write2st64_b32 v129, v132, v130 offset0:58 offset1:59
	ds_write_b32 v129, v135 offset:15616
	s_cmp_eq_u32 s23, 7
	s_cbranch_scc1 .Lm0_noload
	global_load_ushort v168, v201, s[26:27]
	global_load_ushort v169, v201, s[26:27] offset:3584
	v_add_u32_e32 v204, 0x1c00, v201
	v_add_u32_e32 v205, 0x3800, v201
	v_add_u32_e32 v206, 0x5400, v201
	global_load_ushort v170, v204, s[26:27]
	global_load_ushort v171, v204, s[26:27] offset:3584
	global_load_ushort v172, v205, s[26:27]
	global_load_ushort v173, v205, s[26:27] offset:3584
	global_load_ushort v174, v206, s[26:27]
	global_load_ushort v175, v206, s[26:27] offset:3584
	v_add_u32_e32 v204, 0x1000, v202
	global_load_ushort v176, v202, s[14:15]
	global_load_ushort v177, v202, s[14:15] offset:1024
	global_load_ushort v178, v202, s[14:15] offset:2048
	global_load_ushort v179, v202, s[14:15] offset:3072
	global_load_ushort v180, v204, s[14:15]
	global_load_ushort v181, v204, s[14:15] offset:1024
	global_load_ushort v182, v204, s[14:15] offset:2048
	global_load_ushort v183, v204, s[14:15] offset:3072
	global_load_ushort v192, v202, s[16:17]
	global_load_ushort v193, v202, s[16:17] offset:1024
	global_load_ushort v194, v202, s[16:17] offset:2048
	global_load_ushort v195, v202, s[16:17] offset:3072
	global_load_ushort v196, v204, s[16:17]
	global_load_ushort v197, v204, s[16:17] offset:1024
	global_load_ushort v198, v204, s[16:17] offset:2048
	global_load_ushort v199, v204, s[16:17] offset:3072
	v_add_u32_e32 v205, 0x1000, v203
	v_add_u32_e32 v206, 0x2000, v203
	v_add_u32_e32 v207, 0x3000, v203
	global_load_dword v184, v203, s[10:11]
	global_load_dword v185, v203, s[10:11] offset:2048
	global_load_dword v186, v205, s[10:11]
	global_load_dword v187, v205, s[10:11] offset:2048
	global_load_dword v188, v206, s[10:11]
	global_load_dword v189, v206, s[10:11] offset:2048
	global_load_dword v190, v207, s[10:11]
	global_load_dword v191, v207, s[10:11] offset:2048
	v_add_u32_e32 v201, 0x7000, v201
	v_add_u32_e32 v202, 0x2000, v202
	v_add_u32_e32 v203, 0x4000, v203
; #define LAS __attribute__((address_space(3)))
; #define RW_LD_DOT(buf, hb) do { _Pragma("unroll") for (int q_ = 0; q_ < DB; ++q_) kd[buf][q_] = *(const LAS f32x4*)(st + 64 + 4 * (DB * (hb) + q_)); } while (0)
; #define RW_LD_UPD(buf, qb) do { _Pragma("unroll") for (int q_ = 0; q_ < UB; ++q_) { const int qq_ = UB * (qb) + q_; \
;                 wq[buf][q_] = *(const LAS f32x4*)(st + 4 * qq_); bq[buf][q_] = *(const LAS f32x4*)(st + 128 + 4 * qq_); kq[buf][q_] = *(const LAS f32x4*)(st + 192 + 4 * qq_); \
;                 if (MODE == 1) rq[buf][q_] = *(const LAS f32x4*)(st + 256 + 4 * qq_); } } while (0)
; template <int MODE> __device__ __forceinline__ void rwkv_item(const Params& P, int e, int c, int h, LAS float* slab, int lane) {
;     ...
;         for (int s = 0; s < SB; ++s) {
;             const LAS float* st = slab + s * 512;
;             f32x2 aS0 = {0.f, 0.f}, aS1 = {0.f, 0.f}, aC0 = {0.f, 0.f}, aC1 = {0.f, 0.f};
;             constexpr int DB = 4, UB = 2;
;             constexpr int NDB = 16 / DB, NUB = 16 / UB;
;             constexpr int NB = MODE == 1 ? 2 : 1;
;             f32x4 kd[NB][DB];
;             f32x4 wq[NB][UB], bq[NB][UB], kq[NB][UB], rq[NB][MODE == 1 ? UB : 1];
;     ...
;             if (NB == 2) RW_LD_DOT(0, 0);
;             const float v = st[320 + lane];
; #pragma unroll
;             for (int hb = 0; hb < NDB; ++hb) {
;                 if (NB == 2) { if (hb + 1 < NDB) RW_LD_DOT((hb + 1) & 1, hb + 1); else RW_LD_UPD(0, 0); } else RW_LD_DOT(0, hb);
;                 __builtin_amdgcn_sched_barrier(0);
; #pragma unroll
;                 for (int q = 0; q < DB; ++q) {
;                     const int qq = DB * hb + q; const f32x4 k4 = kd[hb & (NB - 1)][q];
;                     aS0 += S2[2 * qq] * (f32x2){k4.x, k4.y}; aS1 += S2[2 * qq + 1] * (f32x2){k4.z, k4.w};
;                     if (MODE == 0) { aC0 += C2[2 * qq] * (f32x2){k4.x, k4.y}; aC1 += C2[2 * qq + 1] * (f32x2){k4.z, k4.w}; }
;                 }
;                 __builtin_amdgcn_sched_barrier(0);
;             }
;             const float nsk = -((aS0.x + aS0.y) + (aS1.x + aS1.y));
;             const float nskC = -((aC0.x + aC0.y) + (aC1.x + aC1.y));
.Lm0_noload:
	s_waitcnt lgkmcnt(0)
	s_mov_b32 s2, 0
.Lm0_step:
	v_add_u32_e32 v152, 0x500, v129
	s_add_i32 s3, s21, s2
	v_add_u32_e32 v152, s2, v152
	v_mov_b32_e32 v233, s3
	ds_read_b32 v152, v152
	ds_read_b128 v[214:217], v233 offset:256
	ds_read_b128 v[234:237], v233 offset:272
	ds_read_b128 v[238:241], v233 offset:288
	ds_read_b128 v[242:245], v233 offset:304
	s_waitcnt lgkmcnt(3)
	v_pk_fma_f32 v[158:159], v[112:113], v[214:215], 0 op_sel_hi:[1,1,0]
	v_pk_fma_f32 v[160:161], v[114:115], v[216:217], 0 op_sel_hi:[1,1,0]
	v_pk_fma_f32 v[162:163], v[124:125], v[214:215], 0 op_sel_hi:[1,1,0]
	v_pk_fma_f32 v[164:165], v[126:127], v[216:217], 0 op_sel_hi:[1,1,0]
	s_waitcnt lgkmcnt(2)
	v_pk_fma_f32 v[158:159], v[104:105], v[234:235], v[158:159]
	v_pk_fma_f32 v[160:161], v[106:107], v[236:237], v[160:161]
	v_pk_fma_f32 v[162:163], v[120:121], v[234:235], v[162:163]
	v_pk_fma_f32 v[164:165], v[122:123], v[236:237], v[164:165]
	s_waitcnt lgkmcnt(1)
	v_pk_fma_f32 v[158:159], v[92:93], v[238:239], v[158:159]
	v_pk_fma_f32 v[160:161], v[94:95], v[240:241], v[160:161]
	v_pk_fma_f32 v[162:163], v[116:117], v[238:239], v[162:163]
	v_pk_fma_f32 v[164:165], v[118:119], v[240:241], v[164:165]
	s_waitcnt lgkmcnt(0)
	v_pk_fma_f32 v[158:159], v[76:77], v[242:243], v[158:159]
	v_pk_fma_f32 v[160:161], v[78:79], v[244:245], v[160:161]
	v_pk_fma_f32 v[162:163], v[108:109], v[242:243], v[162:163]
	v_pk_fma_f32 v[164:165], v[110:111], v[244:245], v[164:165]
	ds_read_b128 v[214:217], v233 offset:320
	ds_read_b128 v[234:237], v233 offset:336
	ds_read_b128 v[238:241], v233 offset:352
	ds_read_b128 v[242:245], v233 offset:368
	s_waitcnt lgkmcnt(3)
	v_pk_fma_f32 v[158:159], v[64:65], v[214:215], v[158:159]
	v_pk_fma_f32 v[160:161], v[66:67], v[216:217], v[160:161]
	v_pk_fma_f32 v[162:163], v[96:97], v[214:215], v[162:163]
	v_pk_fma_f32 v[164:165], v[98:99], v[216:217], v[164:165]
	s_waitcnt lgkmcnt(2)
	v_pk_fma_f32 v[158:159], v[100:101], v[234:235], v[158:159]
	v_pk_fma_f32 v[160:161], v[102:103], v[236:237], v[160:161]
	v_pk_fma_f32 v[162:163], v[80:81], v[234:235], v[162:163]
	v_pk_fma_f32 v[164:165], v[82:83], v[236:237], v[164:165]
	s_waitcnt lgkmcnt(1)
	v_pk_fma_f32 v[158:159], v[88:89], v[238:239], v[158:159]
	v_pk_fma_f32 v[160:161], v[90:91], v[240:241], v[160:161]
	v_pk_fma_f32 v[162:163], v[68:69], v[238:239], v[162:163]
	v_pk_fma_f32 v[164:165], v[70:71], v[240:241], v[164:165]
	s_waitcnt lgkmcnt(0)
	v_pk_fma_f32 v[158:159], v[84:85], v[242:243], v[158:159]
	v_pk_fma_f32 v[160:161], v[86:87], v[244:245], v[160:161]
	v_pk_fma_f32 v[162:163], v[52:53], v[242:243], v[162:163]
	v_pk_fma_f32 v[164:165], v[54:55], v[244:245], v[164:165]
	ds_read_b128 v[214:217], v233 offset:384
	ds_read_b128 v[234:237], v233 offset:400
	ds_read_b128 v[238:241], v233 offset:416
	ds_read_b128 v[242:245], v233 offset:432
	s_waitcnt lgkmcnt(3)
	v_pk_fma_f32 v[158:159], v[72:73], v[214:215], v[158:159]
	v_pk_fma_f32 v[160:161], v[74:75], v[216:217], v[160:161]
	v_pk_fma_f32 v[162:163], v[44:45], v[214:215], v[162:163]
	v_pk_fma_f32 v[164:165], v[46:47], v[216:217], v[164:165]
	s_waitcnt lgkmcnt(2)
	v_pk_fma_f32 v[158:159], v[60:61], v[234:235], v[158:159]
	v_pk_fma_f32 v[160:161], v[62:63], v[236:237], v[160:161]
	v_pk_fma_f32 v[162:163], v[32:33], v[234:235], v[162:163]
	v_pk_fma_f32 v[164:165], v[34:35], v[236:237], v[164:165]
	s_waitcnt lgkmcnt(1)
	v_pk_fma_f32 v[158:159], v[56:57], v[238:239], v[158:159]
	v_pk_fma_f32 v[160:161], v[58:59], v[240:241], v[160:161]
	v_pk_fma_f32 v[162:163], v[24:25], v[238:239], v[162:163]
	v_pk_fma_f32 v[164:165], v[26:27], v[240:241], v[164:165]
	s_waitcnt lgkmcnt(0)
	v_pk_fma_f32 v[158:159], v[48:49], v[242:243], v[158:159]
	v_pk_fma_f32 v[160:161], v[50:51], v[244:245], v[160:161]
	v_pk_fma_f32 v[162:163], v[16:17], v[242:243], v[162:163]
	v_pk_fma_f32 v[164:165], v[18:19], v[244:245], v[164:165]
	ds_read_b128 v[214:217], v233 offset:448
	ds_read_b128 v[234:237], v233 offset:464
	ds_read_b128 v[238:241], v233 offset:480
	ds_read_b128 v[242:245], v233 offset:496
	s_waitcnt lgkmcnt(3)
	v_pk_fma_f32 v[158:159], v[40:41], v[214:215], v[158:159]
	v_pk_fma_f32 v[160:161], v[42:43], v[216:217], v[160:161]
	v_pk_fma_f32 v[162:163], v[12:13], v[214:215], v[162:163]
	v_pk_fma_f32 v[164:165], v[14:15], v[216:217], v[164:165]
	s_waitcnt lgkmcnt(2)
	v_pk_fma_f32 v[158:159], v[36:37], v[234:235], v[158:159]
	v_pk_fma_f32 v[160:161], v[38:39], v[236:237], v[160:161]
	v_pk_fma_f32 v[162:163], v[8:9], v[234:235], v[162:163]
	v_pk_fma_f32 v[164:165], v[10:11], v[236:237], v[164:165]
	s_waitcnt lgkmcnt(1)
	v_pk_fma_f32 v[158:159], v[28:29], v[238:239], v[158:159]
	v_pk_fma_f32 v[160:161], v[30:31], v[240:241], v[160:161]
	v_pk_fma_f32 v[162:163], v[4:5], v[238:239], v[162:163]
	v_pk_fma_f32 v[164:165], v[6:7], v[240:241], v[164:165]
	s_waitcnt lgkmcnt(0)
	v_pk_fma_f32 v[158:159], v[20:21], v[242:243], v[158:159]
	v_pk_fma_f32 v[160:161], v[22:23], v[244:245], v[160:161]
	v_pk_fma_f32 v[162:163], v[0:1], v[242:243], v[162:163]
	v_pk_fma_f32 v[164:165], v[2:3], v[244:245], v[164:165]
	v_mov_b32_e32 v214, v160
	v_mov_b32_e32 v215, v158
	v_mov_b32_e32 v158, v161
	v_pk_add_f32 v[158:159], v[214:215], v[158:159]
	s_nop 0
	v_pk_add_f32 v[214:215], v[158:159], v[158:159] op_sel:[0,1] op_sel_hi:[1,0]
	v_mov_b32_e32 v158, v164
	v_mov_b32_e32 v159, v162
	v_mov_b32_e32 v162, v165
	v_pk_add_f32 v[158:159], v[158:159], v[162:163]
	s_nop 0
	v_pk_add_f32 v[216:217], v[158:159], v[158:159] op_sel:[0,1] op_sel_hi:[1,0]
	ds_read_b128 v[234:237], v233
	ds_read_b128 v[238:241], v233 offset:16
	ds_read_b128 v[242:245], v233 offset:512
	ds_read_b128 v[246:249], v233 offset:768
	ds_read_b128 v[162:165], v233 offset:528
	ds_read_b128 v[158:161], v233 offset:784
	s_waitcnt lgkmcnt(3)
; #define RW_LD_UPD(buf, qb) do { _Pragma("unroll") for (int q_ = 0; q_ < UB; ++q_) { const int qq_ = UB * (qb) + q_; \
;                 wq[buf][q_] = *(const LAS f32x4*)(st + 4 * qq_); bq[buf][q_] = *(const LAS f32x4*)(st + 128 + 4 * qq_); kq[buf][q_] = *(const LAS f32x4*)(st + 192 + 4 * qq_); \
;                 if (MODE == 1) rq[buf][q_] = *(const LAS f32x4*)(st + 256 + 4 * qq_); } } while (0)
; template <int MODE> __device__ __forceinline__ void rwkv_item(const Params& P, int e, int c, int h, LAS float* slab, int lane) {
;     ...
;             f32x2 y0 = {0.f, 0.f}, y1 = {0.f, 0.f};
; #pragma unroll
;             for (int qb = 0; qb < NUB; ++qb) {
;                 if (NB == 2) { if (qb + 1 < NUB) RW_LD_UPD((qb + 1) & 1, qb + 1); } else RW_LD_UPD(0, qb);
;                 __builtin_amdgcn_sched_barrier(0);
; #pragma unroll
;                 for (int q = 0; q < UB; ++q) {
;                     const int qq = UB * qb + q;
;                     const f32x4 w4 = wq[qb & (NB - 1)][q], b4 = bq[qb & (NB - 1)][q], k4 = kq[qb & (NB - 1)][q];
;                     if (MODE == 0) {
;                         S2[2 * qq] = S2[2 * qq] * (f32x2){w4.x, w4.y} + (f32x2){b4.x, b4.y} * nsk;
;                         S2[2 * qq + 1] = S2[2 * qq + 1] * (f32x2){w4.z, w4.w} + (f32x2){b4.z, b4.w} * nsk;
;                         C2[2 * qq] = C2[2 * qq] * (f32x2){w4.x, w4.y} + (f32x2){b4.x, b4.y} * nskC + (f32x2){k4.x, k4.y} * v;
;                         C2[2 * qq + 1] = C2[2 * qq + 1] * (f32x2){w4.z, w4.w} + (f32x2){b4.z, b4.w} * nskC + (f32x2){k4.z, k4.w} * v;
;                     } else {
;                         S2[2 * qq] = S2[2 * qq] * (f32x2){w4.x, w4.y} + (f32x2){b4.x, b4.y} * nsk + (f32x2){k4.x, k4.y} * v;
;                         S2[2 * qq + 1] = S2[2 * qq + 1] * (f32x2){w4.z, w4.w} + (f32x2){b4.z, b4.w} * nsk + (f32x2){k4.z, k4.w} * v;
;                         const f32x4 r4 = rq[qb & (NB - 1)][q]; y0 += S2[2 * qq] * (f32x2){r4.x, r4.y}; y1 += S2[2 * qq + 1] * (f32x2){r4.z, r4.w};
;                     }
;                 }
;                 __builtin_amdgcn_sched_barrier(0);
;             }
	v_pk_mul_f32 v[250:251], v[242:243], v[214:215] op_sel_hi:[1,0] neg_lo:[0,1] neg_hi:[0,1]
	v_pk_mul_f32 v[242:243], v[242:243], v[216:217] op_sel_hi:[1,0] neg_lo:[0,1] neg_hi:[0,1]
	v_pk_fma_f32 v[112:113], v[112:113], v[234:235], v[250:251]
	v_pk_fma_f32 v[124:125], v[124:125], v[234:235], v[242:243]
	v_pk_mul_f32 v[234:235], v[244:245], v[216:217] op_sel_hi:[1,0] neg_lo:[0,1] neg_hi:[0,1]
	v_pk_mul_f32 v[250:251], v[244:245], v[214:215] op_sel_hi:[1,0] neg_lo:[0,1] neg_hi:[0,1]
	v_pk_fma_f32 v[126:127], v[126:127], v[236:237], v[234:235]
	s_waitcnt lgkmcnt(1)
	v_pk_mul_f32 v[234:235], v[214:215], v[162:163] op_sel_hi:[0,1] neg_lo:[1,0] neg_hi:[1,0]
	v_pk_mul_f32 v[162:163], v[216:217], v[162:163] op_sel_hi:[0,1] neg_lo:[1,0] neg_hi:[1,0]
	v_pk_fma_f32 v[120:121], v[120:121], v[238:239], v[162:163]
	v_pk_fma_f32 v[104:105], v[104:105], v[238:239], v[234:235]
	s_waitcnt lgkmcnt(0)
	v_pk_fma_f32 v[120:121], v[152:153], v[158:159], v[120:121] op_sel_hi:[0,1,1]
	v_pk_mul_f32 v[158:159], v[216:217], v[164:165] op_sel_hi:[0,1] neg_lo:[1,0] neg_hi:[1,0]
	v_pk_mul_f32 v[234:235], v[214:215], v[164:165] op_sel_hi:[0,1] neg_lo:[1,0] neg_hi:[1,0]
	v_pk_fma_f32 v[122:123], v[122:123], v[240:241], v[158:159]
	v_pk_fma_f32 v[114:115], v[114:115], v[236:237], v[250:251]
	v_pk_fma_f32 v[124:125], v[152:153], v[246:247], v[124:125] op_sel_hi:[0,1,1]
	v_pk_fma_f32 v[126:127], v[152:153], v[248:249], v[126:127] op_sel_hi:[0,1,1]
	v_pk_fma_f32 v[106:107], v[106:107], v[240:241], v[234:235]
	v_pk_fma_f32 v[122:123], v[152:153], v[160:161], v[122:123] op_sel_hi:[0,1,1]
	ds_read_b128 v[158:161], v233 offset:32
	ds_read_b128 v[162:165], v233 offset:48
	ds_read_b128 v[234:237], v233 offset:544
	ds_read_b128 v[238:241], v233 offset:560
	ds_read_b128 v[242:245], v233 offset:800
	ds_read_b128 v[246:249], v233 offset:816
	s_waitcnt lgkmcnt(3)
	v_pk_mul_f32 v[250:251], v[214:215], v[234:235] op_sel_hi:[0,1] neg_lo:[1,0] neg_hi:[1,0]
	v_pk_mul_f32 v[234:235], v[216:217], v[234:235] op_sel_hi:[0,1] neg_lo:[1,0] neg_hi:[1,0]
	v_pk_fma_f32 v[92:93], v[92:93], v[158:159], v[250:251]
	v_pk_fma_f32 v[116:117], v[116:117], v[158:159], v[234:235]
	v_pk_mul_f32 v[158:159], v[216:217], v[236:237] op_sel_hi:[0,1] neg_lo:[1,0] neg_hi:[1,0]
	v_pk_fma_f32 v[118:119], v[118:119], v[160:161], v[158:159]
	s_waitcnt lgkmcnt(2)
	v_pk_mul_f32 v[158:159], v[214:215], v[238:239] op_sel_hi:[0,1] neg_lo:[1,0] neg_hi:[1,0]
	v_pk_fma_f32 v[76:77], v[76:77], v[162:163], v[158:159]
	v_pk_mul_f32 v[158:159], v[214:215], v[240:241] op_sel_hi:[0,1] neg_lo:[1,0] neg_hi:[1,0]
	v_pk_fma_f32 v[78:79], v[78:79], v[164:165], v[158:159]
	v_pk_mul_f32 v[158:159], v[216:217], v[238:239] op_sel_hi:[0,1] neg_lo:[1,0] neg_hi:[1,0]
	v_pk_fma_f32 v[108:109], v[108:109], v[162:163], v[158:159]
	v_pk_mul_f32 v[158:159], v[216:217], v[240:241] op_sel_hi:[0,1] neg_lo:[1,0] neg_hi:[1,0]
	v_pk_mul_f32 v[250:251], v[214:215], v[236:237] op_sel_hi:[0,1] neg_lo:[1,0] neg_hi:[1,0]
	v_pk_fma_f32 v[110:111], v[110:111], v[164:165], v[158:159]
	v_pk_fma_f32 v[94:95], v[94:95], v[160:161], v[250:251]
	s_waitcnt lgkmcnt(1)
	v_pk_fma_f32 v[116:117], v[152:153], v[242:243], v[116:117] op_sel_hi:[0,1,1]
	v_pk_fma_f32 v[118:119], v[152:153], v[244:245], v[118:119] op_sel_hi:[0,1,1]
	s_waitcnt lgkmcnt(0)
	v_pk_fma_f32 v[108:109], v[152:153], v[246:247], v[108:109] op_sel_hi:[0,1,1]
	v_pk_fma_f32 v[110:111], v[152:153], v[248:249], v[110:111] op_sel_hi:[0,1,1]
	ds_read_b128 v[158:161], v233 offset:64
	ds_read_b128 v[162:165], v233 offset:80
	ds_read_b128 v[234:237], v233 offset:576
	ds_read_b128 v[238:241], v233 offset:592
	ds_read_b128 v[242:245], v233 offset:832
	ds_read_b128 v[246:249], v233 offset:848
	s_waitcnt lgkmcnt(3)
	v_pk_mul_f32 v[250:251], v[214:215], v[234:235] op_sel_hi:[0,1] neg_lo:[1,0] neg_hi:[1,0]
	v_pk_mul_f32 v[234:235], v[216:217], v[234:235] op_sel_hi:[0,1] neg_lo:[1,0] neg_hi:[1,0]
	v_pk_fma_f32 v[64:65], v[64:65], v[158:159], v[250:251]
	v_pk_fma_f32 v[96:97], v[96:97], v[158:159], v[234:235]
	v_pk_mul_f32 v[158:159], v[216:217], v[236:237] op_sel_hi:[0,1] neg_lo:[1,0] neg_hi:[1,0]
	v_pk_fma_f32 v[98:99], v[98:99], v[160:161], v[158:159]
	s_waitcnt lgkmcnt(2)
	v_pk_mul_f32 v[158:159], v[214:215], v[238:239] op_sel_hi:[0,1] neg_lo:[1,0] neg_hi:[1,0]
	v_pk_fma_f32 v[100:101], v[100:101], v[162:163], v[158:159]
	v_pk_mul_f32 v[158:159], v[214:215], v[240:241] op_sel_hi:[0,1] neg_lo:[1,0] neg_hi:[1,0]
	v_pk_fma_f32 v[102:103], v[102:103], v[164:165], v[158:159]
	v_pk_mul_f32 v[158:159], v[216:217], v[238:239] op_sel_hi:[0,1] neg_lo:[1,0] neg_hi:[1,0]
	v_pk_fma_f32 v[80:81], v[80:81], v[162:163], v[158:159]
	v_pk_mul_f32 v[158:159], v[216:217], v[240:241] op_sel_hi:[0,1] neg_lo:[1,0] neg_hi:[1,0]
	v_pk_mul_f32 v[250:251], v[214:215], v[236:237] op_sel_hi:[0,1] neg_lo:[1,0] neg_hi:[1,0]
	v_pk_fma_f32 v[82:83], v[82:83], v[164:165], v[158:159]
	v_pk_fma_f32 v[66:67], v[66:67], v[160:161], v[250:251]
	s_waitcnt lgkmcnt(1)
	v_pk_fma_f32 v[96:97], v[152:153], v[242:243], v[96:97] op_sel_hi:[0,1,1]
	v_pk_fma_f32 v[98:99], v[152:153], v[244:245], v[98:99] op_sel_hi:[0,1,1]
	s_waitcnt lgkmcnt(0)
	v_pk_fma_f32 v[80:81], v[152:153], v[246:247], v[80:81] op_sel_hi:[0,1,1]
	v_pk_fma_f32 v[82:83], v[152:153], v[248:249], v[82:83] op_sel_hi:[0,1,1]
	ds_read_b128 v[158:161], v233 offset:96
	ds_read_b128 v[162:165], v233 offset:112
	ds_read_b128 v[234:237], v233 offset:608
	ds_read_b128 v[238:241], v233 offset:624
	ds_read_b128 v[242:245], v233 offset:864
	ds_read_b128 v[246:249], v233 offset:880
	s_waitcnt lgkmcnt(3)
; #define RW_LD_UPD(buf, qb) do { _Pragma("unroll") for (int q_ = 0; q_ < UB; ++q_) { const int qq_ = UB * (qb) + q_; \
;                 wq[buf][q_] = *(const LAS f32x4*)(st + 4 * qq_); bq[buf][q_] = *(const LAS f32x4*)(st + 128 + 4 * qq_); kq[buf][q_] = *(const LAS f32x4*)(st + 192 + 4 * qq_); \
;                 if (MODE == 1) rq[buf][q_] = *(const LAS f32x4*)(st + 256 + 4 * qq_); } } while (0)
; template <int MODE> __device__ __forceinline__ void rwkv_item(const Params& P, int e, int c, int h, LAS float* slab, int lane) {
;     ...
;             f32x2 y0 = {0.f, 0.f}, y1 = {0.f, 0.f};
; #pragma unroll
;             for (int qb = 0; qb < NUB; ++qb) {
;                 if (NB == 2) { if (qb + 1 < NUB) RW_LD_UPD((qb + 1) & 1, qb + 1); } else RW_LD_UPD(0, qb);
;                 __builtin_amdgcn_sched_barrier(0);
; #pragma unroll
;                 for (int q = 0; q < UB; ++q) {
;                     const int qq = UB * qb + q;
;                     const f32x4 w4 = wq[qb & (NB - 1)][q], b4 = bq[qb & (NB - 1)][q], k4 = kq[qb & (NB - 1)][q];
;                     if (MODE == 0) {
;                         S2[2 * qq] = S2[2 * qq] * (f32x2){w4.x, w4.y} + (f32x2){b4.x, b4.y} * nsk;
;                         S2[2 * qq + 1] = S2[2 * qq + 1] * (f32x2){w4.z, w4.w} + (f32x2){b4.z, b4.w} * nsk;
;                         C2[2 * qq] = C2[2 * qq] * (f32x2){w4.x, w4.y} + (f32x2){b4.x, b4.y} * nskC + (f32x2){k4.x, k4.y} * v;
;                         C2[2 * qq + 1] = C2[2 * qq + 1] * (f32x2){w4.z, w4.w} + (f32x2){b4.z, b4.w} * nskC + (f32x2){k4.z, k4.w} * v;
;                     } else {
;                         S2[2 * qq] = S2[2 * qq] * (f32x2){w4.x, w4.y} + (f32x2){b4.x, b4.y} * nsk + (f32x2){k4.x, k4.y} * v;
;                         S2[2 * qq + 1] = S2[2 * qq + 1] * (f32x2){w4.z, w4.w} + (f32x2){b4.z, b4.w} * nsk + (f32x2){k4.z, k4.w} * v;
;                         const f32x4 r4 = rq[qb & (NB - 1)][q]; y0 += S2[2 * qq] * (f32x2){r4.x, r4.y}; y1 += S2[2 * qq + 1] * (f32x2){r4.z, r4.w};
;                     }
;                 }
;                 __builtin_amdgcn_sched_barrier(0);
;             }
	v_pk_mul_f32 v[250:251], v[214:215], v[234:235] op_sel_hi:[0,1] neg_lo:[1,0] neg_hi:[1,0]
	v_pk_mul_f32 v[234:235], v[216:217], v[234:235] op_sel_hi:[0,1] neg_lo:[1,0] neg_hi:[1,0]
	v_pk_fma_f32 v[88:89], v[88:89], v[158:159], v[250:251]
	v_pk_fma_f32 v[68:69], v[68:69], v[158:159], v[234:235]
	v_pk_mul_f32 v[158:159], v[216:217], v[236:237] op_sel_hi:[0,1] neg_lo:[1,0] neg_hi:[1,0]
	v_pk_fma_f32 v[70:71], v[70:71], v[160:161], v[158:159]
	s_waitcnt lgkmcnt(2)
	v_pk_mul_f32 v[158:159], v[214:215], v[238:239] op_sel_hi:[0,1] neg_lo:[1,0] neg_hi:[1,0]
	v_pk_fma_f32 v[84:85], v[84:85], v[162:163], v[158:159]
	v_pk_mul_f32 v[158:159], v[214:215], v[240:241] op_sel_hi:[0,1] neg_lo:[1,0] neg_hi:[1,0]
	v_pk_fma_f32 v[86:87], v[86:87], v[164:165], v[158:159]
	v_pk_mul_f32 v[158:159], v[216:217], v[238:239] op_sel_hi:[0,1] neg_lo:[1,0] neg_hi:[1,0]
	v_pk_fma_f32 v[52:53], v[52:53], v[162:163], v[158:159]
	v_pk_mul_f32 v[158:159], v[216:217], v[240:241] op_sel_hi:[0,1] neg_lo:[1,0] neg_hi:[1,0]
	v_pk_mul_f32 v[250:251], v[214:215], v[236:237] op_sel_hi:[0,1] neg_lo:[1,0] neg_hi:[1,0]
	v_pk_fma_f32 v[54:55], v[54:55], v[164:165], v[158:159]
	v_pk_fma_f32 v[90:91], v[90:91], v[160:161], v[250:251]
	s_waitcnt lgkmcnt(1)
	v_pk_fma_f32 v[68:69], v[152:153], v[242:243], v[68:69] op_sel_hi:[0,1,1]
	v_pk_fma_f32 v[70:71], v[152:153], v[244:245], v[70:71] op_sel_hi:[0,1,1]
	s_waitcnt lgkmcnt(0)
	v_pk_fma_f32 v[52:53], v[152:153], v[246:247], v[52:53] op_sel_hi:[0,1,1]
	v_pk_fma_f32 v[54:55], v[152:153], v[248:249], v[54:55] op_sel_hi:[0,1,1]
	ds_read_b128 v[158:161], v233 offset:128
	ds_read_b128 v[162:165], v233 offset:144
	ds_read_b128 v[234:237], v233 offset:640
	ds_read_b128 v[238:241], v233 offset:656
	ds_read_b128 v[242:245], v233 offset:896
	ds_read_b128 v[246:249], v233 offset:912
	s_waitcnt lgkmcnt(3)
	v_pk_mul_f32 v[250:251], v[214:215], v[234:235] op_sel_hi:[0,1] neg_lo:[1,0] neg_hi:[1,0]
	v_pk_mul_f32 v[234:235], v[216:217], v[234:235] op_sel_hi:[0,1] neg_lo:[1,0] neg_hi:[1,0]
	v_pk_fma_f32 v[72:73], v[72:73], v[158:159], v[250:251]
	v_pk_fma_f32 v[44:45], v[44:45], v[158:159], v[234:235]
	v_pk_mul_f32 v[158:159], v[216:217], v[236:237] op_sel_hi:[0,1] neg_lo:[1,0] neg_hi:[1,0]
	v_pk_fma_f32 v[46:47], v[46:47], v[160:161], v[158:159]
	s_waitcnt lgkmcnt(2)
	v_pk_mul_f32 v[158:159], v[214:215], v[238:239] op_sel_hi:[0,1] neg_lo:[1,0] neg_hi:[1,0]
	v_pk_fma_f32 v[60:61], v[60:61], v[162:163], v[158:159]
	v_pk_mul_f32 v[158:159], v[214:215], v[240:241] op_sel_hi:[0,1] neg_lo:[1,0] neg_hi:[1,0]
	v_pk_fma_f32 v[62:63], v[62:63], v[164:165], v[158:159]
	v_pk_mul_f32 v[158:159], v[216:217], v[238:239] op_sel_hi:[0,1] neg_lo:[1,0] neg_hi:[1,0]
	v_pk_fma_f32 v[32:33], v[32:33], v[162:163], v[158:159]
	v_pk_mul_f32 v[158:159], v[216:217], v[240:241] op_sel_hi:[0,1] neg_lo:[1,0] neg_hi:[1,0]
	v_pk_mul_f32 v[250:251], v[214:215], v[236:237] op_sel_hi:[0,1] neg_lo:[1,0] neg_hi:[1,0]
	v_pk_fma_f32 v[34:35], v[34:35], v[164:165], v[158:159]
	v_pk_fma_f32 v[74:75], v[74:75], v[160:161], v[250:251]
	s_waitcnt lgkmcnt(1)
	v_pk_fma_f32 v[44:45], v[152:153], v[242:243], v[44:45] op_sel_hi:[0,1,1]
	v_pk_fma_f32 v[46:47], v[152:153], v[244:245], v[46:47] op_sel_hi:[0,1,1]
	s_waitcnt lgkmcnt(0)
	v_pk_fma_f32 v[32:33], v[152:153], v[246:247], v[32:33] op_sel_hi:[0,1,1]
	v_pk_fma_f32 v[34:35], v[152:153], v[248:249], v[34:35] op_sel_hi:[0,1,1]
	ds_read_b128 v[158:161], v233 offset:160
	ds_read_b128 v[162:165], v233 offset:176
	ds_read_b128 v[234:237], v233 offset:672
	ds_read_b128 v[238:241], v233 offset:688
	ds_read_b128 v[242:245], v233 offset:928
	ds_read_b128 v[246:249], v233 offset:944
	s_waitcnt lgkmcnt(3)
	v_pk_mul_f32 v[250:251], v[214:215], v[234:235] op_sel_hi:[0,1] neg_lo:[1,0] neg_hi:[1,0]
	v_pk_mul_f32 v[234:235], v[216:217], v[234:235] op_sel_hi:[0,1] neg_lo:[1,0] neg_hi:[1,0]
	v_pk_fma_f32 v[56:57], v[56:57], v[158:159], v[250:251]
	v_pk_fma_f32 v[24:25], v[24:25], v[158:159], v[234:235]
	v_pk_mul_f32 v[158:159], v[216:217], v[236:237] op_sel_hi:[0,1] neg_lo:[1,0] neg_hi:[1,0]
	v_pk_fma_f32 v[26:27], v[26:27], v[160:161], v[158:159]
	s_waitcnt lgkmcnt(2)
	v_pk_mul_f32 v[158:159], v[214:215], v[238:239] op_sel_hi:[0,1] neg_lo:[1,0] neg_hi:[1,0]
	v_pk_fma_f32 v[48:49], v[48:49], v[162:163], v[158:159]
	v_pk_mul_f32 v[158:159], v[214:215], v[240:241] op_sel_hi:[0,1] neg_lo:[1,0] neg_hi:[1,0]
	v_pk_fma_f32 v[50:51], v[50:51], v[164:165], v[158:159]
	v_pk_mul_f32 v[158:159], v[216:217], v[238:239] op_sel_hi:[0,1] neg_lo:[1,0] neg_hi:[1,0]
	v_pk_fma_f32 v[16:17], v[16:17], v[162:163], v[158:159]
	v_pk_mul_f32 v[158:159], v[216:217], v[240:241] op_sel_hi:[0,1] neg_lo:[1,0] neg_hi:[1,0]
	v_pk_mul_f32 v[250:251], v[214:215], v[236:237] op_sel_hi:[0,1] neg_lo:[1,0] neg_hi:[1,0]
	v_pk_fma_f32 v[18:19], v[18:19], v[164:165], v[158:159]
	v_pk_fma_f32 v[58:59], v[58:59], v[160:161], v[250:251]
	s_waitcnt lgkmcnt(1)
	v_pk_fma_f32 v[24:25], v[152:153], v[242:243], v[24:25] op_sel_hi:[0,1,1]
	v_pk_fma_f32 v[26:27], v[152:153], v[244:245], v[26:27] op_sel_hi:[0,1,1]
	s_waitcnt lgkmcnt(0)
	v_pk_fma_f32 v[16:17], v[152:153], v[246:247], v[16:17] op_sel_hi:[0,1,1]
	v_pk_fma_f32 v[18:19], v[152:153], v[248:249], v[18:19] op_sel_hi:[0,1,1]
	ds_read_b128 v[158:161], v233 offset:192
	ds_read_b128 v[162:165], v233 offset:208
	ds_read_b128 v[234:237], v233 offset:704
	ds_read_b128 v[238:241], v233 offset:720
	ds_read_b128 v[242:245], v233 offset:960
	ds_read_b128 v[246:249], v233 offset:976
	s_waitcnt lgkmcnt(3)
; template <int MODE> __device__ __forceinline__ void rwkv_item(const Params& P, int e, int c, int h, LAS float* slab, int lane) {
;     ...
;             f32x2 y0 = {0.f, 0.f}, y1 = {0.f, 0.f};
; #pragma unroll
;             for (int qb = 0; qb < NUB; ++qb) {
;                 if (NB == 2) { if (qb + 1 < NUB) RW_LD_UPD((qb + 1) & 1, qb + 1); } else RW_LD_UPD(0, qb);
;                 __builtin_amdgcn_sched_barrier(0);
; #pragma unroll
;                 for (int q = 0; q < UB; ++q) {
;                     const int qq = UB * qb + q;
;                     const f32x4 w4 = wq[qb & (NB - 1)][q], b4 = bq[qb & (NB - 1)][q], k4 = kq[qb & (NB - 1)][q];
;                     if (MODE == 0) {
;                         S2[2 * qq] = S2[2 * qq] * (f32x2){w4.x, w4.y} + (f32x2){b4.x, b4.y} * nsk;
;                         S2[2 * qq + 1] = S2[2 * qq + 1] * (f32x2){w4.z, w4.w} + (f32x2){b4.z, b4.w} * nsk;
;                         C2[2 * qq] = C2[2 * qq] * (f32x2){w4.x, w4.y} + (f32x2){b4.x, b4.y} * nskC + (f32x2){k4.x, k4.y} * v;
;                         C2[2 * qq + 1] = C2[2 * qq + 1] * (f32x2){w4.z, w4.w} + (f32x2){b4.z, b4.w} * nskC + (f32x2){k4.z, k4.w} * v;
;                     } else {
;                         S2[2 * qq] = S2[2 * qq] * (f32x2){w4.x, w4.y} + (f32x2){b4.x, b4.y} * nsk + (f32x2){k4.x, k4.y} * v;
;                         S2[2 * qq + 1] = S2[2 * qq + 1] * (f32x2){w4.z, w4.w} + (f32x2){b4.z, b4.w} * nsk + (f32x2){k4.z, k4.w} * v;
;                         const f32x4 r4 = rq[qb & (NB - 1)][q]; y0 += S2[2 * qq] * (f32x2){r4.x, r4.y}; y1 += S2[2 * qq + 1] * (f32x2){r4.z, r4.w};
;                     }
;                 }
;                 __builtin_amdgcn_sched_barrier(0);
;             }
;     ...
;     if (MODE == 0) {
; #pragma unroll
;         for (int q = 0; q < 16; ++q) {
;             *(f32x4*)(MCM + rowoff + 4 * q) = (f32x4){S2[2 * q].x, S2[2 * q].y, S2[2 * q + 1].x, S2[2 * q + 1].y};
;             *(f32x4*)(MCC + rowoff + 4 * q) = (f32x4){C2[2 * q].x, C2[2 * q].y, C2[2 * q + 1].x, C2[2 * q + 1].y};
;         }
;     }
	v_pk_mul_f32 v[250:251], v[214:215], v[234:235] op_sel_hi:[0,1] neg_lo:[1,0] neg_hi:[1,0]
	v_pk_mul_f32 v[234:235], v[216:217], v[234:235] op_sel_hi:[0,1] neg_lo:[1,0] neg_hi:[1,0]
	v_pk_fma_f32 v[40:41], v[40:41], v[158:159], v[250:251]
	v_pk_fma_f32 v[12:13], v[12:13], v[158:159], v[234:235]
	v_pk_mul_f32 v[158:159], v[216:217], v[236:237] op_sel_hi:[0,1] neg_lo:[1,0] neg_hi:[1,0]
	v_pk_fma_f32 v[14:15], v[14:15], v[160:161], v[158:159]
	s_waitcnt lgkmcnt(2)
	v_pk_mul_f32 v[158:159], v[214:215], v[238:239] op_sel_hi:[0,1] neg_lo:[1,0] neg_hi:[1,0]
	v_pk_fma_f32 v[36:37], v[36:37], v[162:163], v[158:159]
	v_pk_mul_f32 v[158:159], v[214:215], v[240:241] op_sel_hi:[0,1] neg_lo:[1,0] neg_hi:[1,0]
	v_pk_fma_f32 v[38:39], v[38:39], v[164:165], v[158:159]
	v_pk_mul_f32 v[158:159], v[216:217], v[238:239] op_sel_hi:[0,1] neg_lo:[1,0] neg_hi:[1,0]
	v_pk_fma_f32 v[8:9], v[8:9], v[162:163], v[158:159]
	v_pk_mul_f32 v[158:159], v[216:217], v[240:241] op_sel_hi:[0,1] neg_lo:[1,0] neg_hi:[1,0]
	v_pk_mul_f32 v[250:251], v[214:215], v[236:237] op_sel_hi:[0,1] neg_lo:[1,0] neg_hi:[1,0]
	v_pk_fma_f32 v[10:11], v[10:11], v[164:165], v[158:159]
	v_pk_fma_f32 v[42:43], v[42:43], v[160:161], v[250:251]
	s_waitcnt lgkmcnt(1)
	v_pk_fma_f32 v[12:13], v[152:153], v[242:243], v[12:13] op_sel_hi:[0,1,1]
	v_pk_fma_f32 v[14:15], v[152:153], v[244:245], v[14:15] op_sel_hi:[0,1,1]
	s_waitcnt lgkmcnt(0)
	v_pk_fma_f32 v[8:9], v[152:153], v[246:247], v[8:9] op_sel_hi:[0,1,1]
	v_pk_fma_f32 v[10:11], v[152:153], v[248:249], v[10:11] op_sel_hi:[0,1,1]
	ds_read_b128 v[158:161], v233 offset:224
	ds_read_b128 v[162:165], v233 offset:240
	ds_read_b128 v[234:237], v233 offset:736
	ds_read_b128 v[238:241], v233 offset:752
	ds_read_b128 v[242:245], v233 offset:992
	ds_read_b128 v[246:249], v233 offset:1008
	s_waitcnt lgkmcnt(3)
	v_pk_mul_f32 v[250:251], v[214:215], v[234:235] op_sel_hi:[0,1] neg_lo:[1,0] neg_hi:[1,0]
	v_pk_mul_f32 v[234:235], v[216:217], v[234:235] op_sel_hi:[0,1] neg_lo:[1,0] neg_hi:[1,0]
	v_pk_fma_f32 v[28:29], v[28:29], v[158:159], v[250:251]
	v_pk_fma_f32 v[4:5], v[4:5], v[158:159], v[234:235]
	v_pk_mul_f32 v[158:159], v[216:217], v[236:237] op_sel_hi:[0,1] neg_lo:[1,0] neg_hi:[1,0]
	v_pk_fma_f32 v[6:7], v[6:7], v[160:161], v[158:159]
	s_waitcnt lgkmcnt(2)
	v_pk_mul_f32 v[158:159], v[214:215], v[238:239] op_sel_hi:[0,1] neg_lo:[1,0] neg_hi:[1,0]
	v_pk_fma_f32 v[20:21], v[20:21], v[162:163], v[158:159]
	v_pk_mul_f32 v[158:159], v[214:215], v[240:241] op_sel_hi:[0,1] neg_lo:[1,0] neg_hi:[1,0]
	v_pk_fma_f32 v[22:23], v[22:23], v[164:165], v[158:159]
	v_pk_mul_f32 v[158:159], v[216:217], v[238:239] op_sel_hi:[0,1] neg_lo:[1,0] neg_hi:[1,0]
	v_pk_fma_f32 v[0:1], v[0:1], v[162:163], v[158:159]
	v_pk_mul_f32 v[158:159], v[216:217], v[240:241] op_sel_hi:[0,1] neg_lo:[1,0] neg_hi:[1,0]
	v_pk_mul_f32 v[250:251], v[214:215], v[236:237] op_sel_hi:[0,1] neg_lo:[1,0] neg_hi:[1,0]
	v_pk_fma_f32 v[2:3], v[2:3], v[164:165], v[158:159]
	v_pk_fma_f32 v[30:31], v[30:31], v[160:161], v[250:251]
	s_waitcnt lgkmcnt(1)
	v_pk_fma_f32 v[4:5], v[152:153], v[242:243], v[4:5] op_sel_hi:[0,1,1]
	v_pk_fma_f32 v[6:7], v[152:153], v[244:245], v[6:7] op_sel_hi:[0,1,1]
	s_waitcnt lgkmcnt(0)
	v_pk_fma_f32 v[0:1], v[152:153], v[246:247], v[0:1] op_sel_hi:[0,1,1]
	v_pk_fma_f32 v[2:3], v[152:153], v[248:249], v[2:3] op_sel_hi:[0,1,1]
	s_addk_i32 s2, 0x800
	s_cmpk_eq_i32 s2, 0x4000
	s_cbranch_scc0 .Lm0_step
	s_add_i32 s23, s23, 1
	s_cmp_eq_u32 s23, 8
	s_cbranch_scc0 .Lm0_sub
	s_lshl_b32 s2, s20, 6
	v_or_b32_e32 v204, s2, v128
	v_lshlrev_b32_e32 v204, 8, v204
	s_add_i32 s20, s20, s58
	global_store_dwordx4 v204, v[112:115], s[18:19]
	global_store_dwordx4 v204, v[124:127], s[8:9]
	global_store_dwordx4 v204, v[104:107], s[18:19] offset:16
	global_store_dwordx4 v204, v[120:123], s[8:9] offset:16
	global_store_dwordx4 v204, v[92:95], s[18:19] offset:32
	global_store_dwordx4 v204, v[116:119], s[8:9] offset:32
	global_store_dwordx4 v204, v[76:79], s[18:19] offset:48
	global_store_dwordx4 v204, v[108:111], s[8:9] offset:48
	global_store_dwordx4 v204, v[64:67], s[18:19] offset:64
	global_store_dwordx4 v204, v[96:99], s[8:9] offset:64
	global_store_dwordx4 v204, v[100:103], s[18:19] offset:80
	global_store_dwordx4 v204, v[80:83], s[8:9] offset:80
	global_store_dwordx4 v204, v[88:91], s[18:19] offset:96
	global_store_dwordx4 v204, v[68:71], s[8:9] offset:96
	global_store_dwordx4 v204, v[84:87], s[18:19] offset:112
	global_store_dwordx4 v204, v[52:55], s[8:9] offset:112
	global_store_dwordx4 v204, v[72:75], s[18:19] offset:128
	global_store_dwordx4 v204, v[44:47], s[8:9] offset:128
	global_store_dwordx4 v204, v[60:63], s[18:19] offset:144
	global_store_dwordx4 v204, v[32:35], s[8:9] offset:144
	global_store_dwordx4 v204, v[56:59], s[18:19] offset:160
	global_store_dwordx4 v204, v[24:27], s[8:9] offset:160
	global_store_dwordx4 v204, v[48:51], s[18:19] offset:176
	global_store_dwordx4 v204, v[16:19], s[8:9] offset:176
	global_store_dwordx4 v204, v[40:43], s[18:19] offset:192
	global_store_dwordx4 v204, v[12:15], s[8:9] offset:192
	global_store_dwordx4 v204, v[36:39], s[18:19] offset:208
	global_store_dwordx4 v204, v[8:11], s[8:9] offset:208
	global_store_dwordx4 v204, v[28:31], s[18:19] offset:224
	global_store_dwordx4 v204, v[4:7], s[8:9] offset:224
	global_store_dwordx4 v204, v[20:23], s[18:19] offset:240
	global_store_dwordx4 v204, v[0:3], s[8:9] offset:240
	s_cmpk_gt_i32 s20, 0x7ff
	s_cbranch_scc0 .LBB0_262
	v_mov_b32_e32 v210, 1
	v_mov_b64_e32 v[244:245], 0x180
	v_mov_b64_e32 v[246:247], 0x80
	v_mov_b64_e32 v[248:249], 0x7f
